# DSA score loop: next-tile indexer-key loads waited at the end of the tile body instead of inside the current tile's MFMA chain
# baseline (speedup 1.0000x reference)
.LBB0_190:
	s_or_b64 exec, exec, s[28:29]
	s_lshl_b32 s29, s38, 3
	v_readfirstlane_b32 s28, v147
	s_sub_i32 s46, 0xff8, s29
	s_and_b64 vcc, exec, s[26:27]
	s_lshr_b32 s47, s28, 6
	s_cbranch_vccnz .LBB0_196
	s_sub_i32 s29, 0x1018, s29
	s_lshr_b32 s34, s29, 5
	s_cmp_ge_u32 s47, s34
	s_cbranch_scc1 .LBB0_196
	s_add_i32 s29, s46, s3
	v_or_b32_e32 v150, s29, v168
	v_lshlrev_b64 v[2:3], 10, v[150:151]
	v_lshl_add_u64 v[2:3], v[152:153], 0, v[2:3]
	v_add_co_u32_e32 v6, vcc, 0x1000, v2
	v_or_b32_e32 v150, s29, v170
	global_load_dwordx4 v[34:37], v[2:3], off
	global_load_dwordx4 v[38:41], v[2:3], off offset:32
	global_load_dwordx4 v[42:45], v[2:3], off offset:64
	global_load_dwordx4 v[46:49], v[2:3], off offset:96
	v_addc_co_u32_e32 v7, vcc, 0, v3, vcc
	v_lshlrev_b64 v[2:3], 5, v[150:151]
	v_lshl_add_u64 v[2:3], s[64:65], 0, v[2:3]
	global_load_dwordx4 v[50:53], v[6:7], off
	global_load_dwordx4 v[54:57], v[6:7], off offset:32
	global_load_dwordx4 v[58:61], v[2:3], off offset:48
	global_load_dwordx4 v[62:65], v[2:3], off offset:32
	global_load_dwordx4 v[66:69], v[2:3], off offset:16
	global_load_dwordx4 v[70:73], v[2:3], off
	global_load_dwordx4 v[74:77], v[2:3], off offset:176
	global_load_dwordx4 v[78:81], v[2:3], off offset:160
	global_load_dwordx4 v[82:85], v[2:3], off offset:144
	global_load_dwordx4 v[86:89], v[2:3], off offset:128
	s_lshl_b32 s38, s47, 5
	s_lshl_b64 s[42:43], s[38:39], 7
	v_lshl_add_u64 v[8:9], v[154:155], 0, s[42:43]
	global_load_dwordx4 v[118:121], v[8:9], off offset:64
	global_load_dwordx4 v[114:117], v[8:9], off offset:96
	global_load_dwordx4 v[2:5], v[8:9], off
	global_load_dwordx4 v[122:125], v[8:9], off offset:32
	global_load_dwordx4 v[90:93], v[6:7], off offset:64
	global_load_dwordx4 v[94:97], v[6:7], off offset:96
	s_lshl_b64 s[28:29], s[28:29], 6
	s_and_b32 s29, s29, 63
	s_and_b32 s28, s28, 0xfffff000
	v_or_b32_e32 v128, s46, v170
	v_or_b32_e32 v129, s46, v171
	v_or_b32_e32 v130, s46, v172
	v_or_b32_e32 v131, s46, v173
	v_lshl_add_u32 v132, s47, 6, v192
	s_mov_b32 s35, s47
	v_or_b32_e32 v133, s38, v149
	v_lshl_add_u64 v[126:127], v[164:165], 0, s[28:29]
	s_waitcnt vmcnt(5)
	v_mov_b64_e32 v[102:103], v[118:119]
	s_waitcnt vmcnt(4)
	v_mov_b64_e32 v[98:99], v[114:115]
	s_waitcnt vmcnt(3)
	v_mov_b64_e32 v[112:113], v[4:5]
	s_waitcnt vmcnt(2)
	v_mov_b64_e32 v[106:107], v[122:123]
	v_mov_b64_e32 v[100:101], v[116:117]
	v_mov_b64_e32 v[104:105], v[120:121]
	v_mov_b64_e32 v[108:109], v[124:125]
	v_mov_b64_e32 v[110:111], v[2:3]
	s_waitcnt vmcnt(0)
	s_branch .LBB0_194
.LBB0_193:
	v_mfma_f32_32x32x16_bf16 v[18:33], v[34:37], v[2:5], 0
	s_mov_b64 s[42:43], 0x4000
	v_lshl_add_u64 v[126:127], v[126:127], 0, s[42:43]
	v_mfma_f32_32x32x16_bf16 v[18:33], v[38:41], v[122:125], v[18:33]
	v_mfma_f32_32x32x16_bf16 v[2:17], v[50:53], v[2:5], 0
	v_mfma_f32_32x32x16_bf16 v[18:33], v[42:45], v[118:121], v[18:33]
	v_mfma_f32_32x32x16_bf16 v[2:17], v[54:57], v[122:125], v[2:17]
	v_mfma_f32_32x32x16_bf16 v[18:33], v[46:49], v[114:117], v[18:33]
	v_mfma_f32_32x32x16_bf16 v[2:17], v[90:93], v[118:121], v[2:17]
	s_nop 9
	v_max_f32_e32 v18, v18, v18
	v_max_f32_e32 v26, v26, v26
	v_max_f32_e32 v19, v19, v19
	v_max_f32_e32 v27, v27, v27
	v_max_f32_e32 v18, 0, v18
	v_max_f32_e32 v26, 0, v26
	v_max_f32_e32 v19, 0, v19
	v_max_f32_e32 v27, 0, v27
	v_pk_mul_f32 v[18:19], v[70:71], v[18:19]
	v_pk_mul_f32 v[26:27], v[62:63], v[26:27]
	v_max_f32_e32 v20, v20, v20
	v_max_f32_e32 v28, v28, v28
	v_max_f32_e32 v21, v21, v21
	v_max_f32_e32 v29, v29, v29
	v_mfma_f32_32x32x16_bf16 v[2:17], v[94:97], v[114:117], v[2:17]
	v_max_f32_e32 v20, 0, v20
	v_max_f32_e32 v28, 0, v28
	v_max_f32_e32 v21, 0, v21
	v_max_f32_e32 v29, 0, v29
	v_mov_b32_e32 v114, v26
	v_mov_b32_e32 v115, v18
	v_pk_mul_f32 v[20:21], v[72:73], v[20:21]
	v_pk_mul_f32 v[28:29], v[64:65], v[28:29]
	v_max_f32_e32 v22, v22, v22
	v_max_f32_e32 v30, v30, v30
	v_max_f32_e32 v23, v23, v23
	v_max_f32_e32 v31, v31, v31
	v_pk_add_f32 v[114:115], v[114:115], 0 op_sel_hi:[1,0]
	v_mov_b32_e32 v18, v27
	v_max_f32_e32 v22, 0, v22
	v_max_f32_e32 v30, 0, v30
	v_max_f32_e32 v23, 0, v23
	v_max_f32_e32 v31, 0, v31
	v_pk_add_f32 v[18:19], v[18:19], v[114:115]
	v_mov_b32_e32 v26, v28
	v_mov_b32_e32 v27, v20
	v_pk_mul_f32 v[22:23], v[66:67], v[22:23]
	v_pk_mul_f32 v[30:31], v[58:59], v[30:31]
	v_max_f32_e32 v24, v24, v24
	v_max_f32_e32 v32, v32, v32
	v_max_f32_e32 v25, v25, v25
	v_max_f32_e32 v33, v33, v33
	v_pk_add_f32 v[18:19], v[26:27], v[18:19]
	v_mov_b32_e32 v20, v29
	v_max_f32_e32 v24, 0, v24
	v_max_f32_e32 v32, 0, v32
	v_max_f32_e32 v25, 0, v25
	v_max_f32_e32 v33, 0, v33
	v_pk_add_f32 v[18:19], v[20:21], v[18:19]
	v_mov_b32_e32 v20, v30
	v_mov_b32_e32 v21, v22
	v_pk_mul_f32 v[24:25], v[68:69], v[24:25]
	v_pk_mul_f32 v[32:33], v[60:61], v[32:33]
	v_pk_add_f32 v[18:19], v[20:21], v[18:19]
	v_mov_b32_e32 v22, v31
	v_pk_add_f32 v[18:19], v[22:23], v[18:19]
	v_mov_b32_e32 v20, v32
	v_mov_b32_e32 v21, v24
	v_pk_add_f32 v[18:19], v[20:21], v[18:19]
	v_mov_b32_e32 v24, v33
	v_pk_add_f32 v[18:19], v[24:25], v[18:19]
	v_max_f32_e32 v2, v2, v2
	v_pk_add_f32 v[18:19], v[18:19], 0 op_sel_hi:[1,0]
	v_max_f32_e32 v10, v10, v10
	v_bfe_u32 v20, v19, 13, 18
	v_med3_u32 v20, v20, s44, v197
	v_add_u32_e32 v21, 0x5400, v20
	v_sub_u32_e32 v20, 0x22bff, v20
	v_or_b32_e32 v21, 0x8000, v21
	v_max_u32_e32 v20, 1, v20
	v_cmp_gt_i32_e32 vcc, 0, v19
	v_max_f32_e32 v3, v3, v3
	v_max_f32_e32 v11, v11, v11
	v_cndmask_b32_e32 v19, v21, v20, vcc
	v_cmp_le_u32_e32 vcc, v133, v128
	v_max_f32_e32 v2, 0, v2
	v_max_f32_e32 v10, 0, v10
	v_cndmask_b32_e32 v19, 0, v19, vcc
	ds_write_b16 v132, v19
	v_bfe_u32 v19, v18, 13, 18
	v_med3_u32 v19, v19, s44, v197
	v_add_u32_e32 v20, 0x5400, v19
	v_sub_u32_e32 v19, 0x22bff, v19
	v_or_b32_e32 v20, 0x8000, v20
	v_max_u32_e32 v19, 1, v19
	v_cmp_gt_i32_e32 vcc, 0, v18
	v_max_f32_e32 v3, 0, v3
	v_max_f32_e32 v11, 0, v11
	v_cndmask_b32_e32 v18, v20, v19, vcc
	v_cmp_le_u32_e32 vcc, v133, v129
	v_pk_mul_f32 v[2:3], v[86:87], v[2:3]
	v_pk_mul_f32 v[10:11], v[78:79], v[10:11]
	v_max_f32_e32 v4, v4, v4
	v_max_f32_e32 v12, v12, v12
	v_max_f32_e32 v5, v5, v5
	v_max_f32_e32 v13, v13, v13
	v_cndmask_b32_e32 v18, 0, v18, vcc
	v_max_f32_e32 v4, 0, v4
	v_max_f32_e32 v12, 0, v12
	v_max_f32_e32 v5, 0, v5
	v_max_f32_e32 v13, 0, v13
	ds_write_b16 v132, v18 offset:8192
	v_mov_b32_e32 v18, v10
	v_mov_b32_e32 v19, v2
	v_pk_mul_f32 v[4:5], v[88:89], v[4:5]
	v_pk_mul_f32 v[12:13], v[80:81], v[12:13]
	v_max_f32_e32 v6, v6, v6
	v_max_f32_e32 v14, v14, v14
	v_max_f32_e32 v7, v7, v7
	v_max_f32_e32 v15, v15, v15
	v_pk_add_f32 v[18:19], v[18:19], 0 op_sel_hi:[1,0]
	v_mov_b32_e32 v2, v11
	v_max_f32_e32 v6, 0, v6
	v_max_f32_e32 v14, 0, v14
	v_max_f32_e32 v7, 0, v7
	v_max_f32_e32 v15, 0, v15
	v_pk_add_f32 v[2:3], v[2:3], v[18:19]
	v_mov_b32_e32 v10, v12
	v_mov_b32_e32 v11, v4
	v_pk_mul_f32 v[6:7], v[82:83], v[6:7]
	v_pk_mul_f32 v[14:15], v[74:75], v[14:15]
	v_max_f32_e32 v8, v8, v8
	v_max_f32_e32 v16, v16, v16
	v_max_f32_e32 v9, v9, v9
	v_max_f32_e32 v17, v17, v17
	v_pk_add_f32 v[2:3], v[10:11], v[2:3]
	v_mov_b32_e32 v4, v13
	v_max_f32_e32 v8, 0, v8
	v_max_f32_e32 v16, 0, v16
	v_max_f32_e32 v9, 0, v9
	v_max_f32_e32 v17, 0, v17
	v_pk_add_f32 v[2:3], v[4:5], v[2:3]
	v_mov_b32_e32 v4, v14
	v_mov_b32_e32 v5, v6
	v_pk_mul_f32 v[8:9], v[84:85], v[8:9]
	v_pk_mul_f32 v[16:17], v[76:77], v[16:17]
	v_pk_add_f32 v[2:3], v[4:5], v[2:3]
	v_mov_b32_e32 v6, v15
	v_pk_add_f32 v[2:3], v[6:7], v[2:3]
	v_mov_b32_e32 v4, v16
	v_mov_b32_e32 v5, v8
	v_pk_add_f32 v[2:3], v[4:5], v[2:3]
	v_mov_b32_e32 v8, v17
	v_pk_add_f32 v[2:3], v[8:9], v[2:3]
	s_waitcnt vmcnt(0)
	v_mov_b64_e32 v[124:125], v[108:109]
	v_mov_b64_e32 v[122:123], v[106:107]
	v_mov_b64_e32 v[120:121], v[104:105]
	v_pk_add_f32 v[2:3], v[2:3], 0 op_sel_hi:[1,0]
	v_mov_b64_e32 v[116:117], v[100:101]
	v_bfe_u32 v4, v3, 13, 18
	v_med3_u32 v4, v4, s44, v197
	v_add_u32_e32 v5, 0x5400, v4
	v_sub_u32_e32 v4, 0x22bff, v4
	v_or_b32_e32 v5, 0x8000, v5
	v_max_u32_e32 v4, 1, v4
	v_cmp_gt_i32_e32 vcc, 0, v3
	v_mov_b64_e32 v[118:119], v[102:103]
	v_mov_b64_e32 v[114:115], v[98:99]
	v_cndmask_b32_e32 v3, v5, v4, vcc
	v_cmp_le_u32_e32 vcc, v133, v130
	s_nop 1
	v_cndmask_b32_e32 v3, 0, v3, vcc
	ds_write_b16 v132, v3 offset:32768
	v_bfe_u32 v3, v2, 13, 18
	v_med3_u32 v3, v3, s44, v197
	v_add_u32_e32 v4, 0x5400, v3
	v_sub_u32_e32 v3, 0x22bff, v3
	v_or_b32_e32 v4, 0x8000, v4
	v_max_u32_e32 v3, 1, v3
	v_cmp_gt_i32_e32 vcc, 0, v2
	s_nop 1
	v_cndmask_b32_e32 v2, v4, v3, vcc
	v_cmp_le_u32_e32 vcc, v133, v131
	v_add_u32_e32 v133, 0x80, v133
	s_nop 0
	v_cndmask_b32_e32 v2, 0, v2, vcc
	ds_write_b16 v132, v2 offset:40960
	v_mov_b64_e32 v[2:3], v[110:111]
	v_add_u32_e32 v132, 0x100, v132
	s_andn2_b64 vcc, exec, s[28:29]
	v_mov_b64_e32 v[4:5], v[112:113]
	s_cbranch_vccz .LBB0_196
